# FoX QK order: the four MFMAs of key rows 0-31 first; their scale+gate FMAs issue between the MFMAs of rows 32-63
# baseline (speedup 1.0000x reference)
; __device__ __forceinline__ f32x16 mfma32(bf16x8 a, bf16x8 b, f32x16 c) { return __builtin_amdgcn_mfma_f32_32x32x16_bf16(a, b, c, 0, 0, 0); }
; template <int MODE> ...
;     ...
;         const lptr Kt = L + A_KT + buf * 9216, Vt = L + A_VT + vcur * 12288;
;         f32x16 s0, s1;
; #pragma unroll
;         for (int s4 = 0; s4 < 4; ++s4) {
;             const bf16x8 a0 = lds_ld<bf16x8>(Kt + n * KP + s4 * 32 + hl * 16);
;             const bf16x8 a1 = lds_ld<bf16x8>(Kt + (32 + n) * KP + s4 * 32 + hl * 16);
;             if (s4 == 0) { s0 = mfma32(a0, qf[0], negm); s1 = mfma32(a1, qf[0], negm); }
;             else { s0 = mfma32(a0, qf[s4], s0); s1 = mfma32(a1, qf[s4], s1); }
;         }
;         const int kbase = 64 * kt + 4 * hl;
;         const bool far = (MODE == MODE_WIN || MODE == MODE_SEL) ? (wtmin - (64 * kt + 63) >= 128) : false;
;         const bool fmask = (MODE == MODE_FOX) ? (64 * kt + 63 > wtmin) : false;
;         const bool clean = (MODE == MODE_WIN) ? (far && (wtmax - 64 * kt < W)) : false;
;         const float mref = (MODE == MODE_CMP2) ? mfix : ((m == -INFINITY) ? 0.f : m);
;         if (MODE == MODE_FOX) {
; #pragma unroll
;             for (int kb = 0; kb < 2; ++kb)
; #pragma unroll
;                 for (int a = 0; a < 4; ++a) {
;                     const f32x4 c4 = lds_ld<f32x4>(L + A_CB + buf * 256 + (32 * kb + 8 * a + 4 * hl) * 4);
; #pragma unroll
;                     for (int e = 0; e < 4; ++e) { const int r = 4 * a + e; if (kb) s1[r] = s1[r] * SC2 + c4[e]; else s0[r] = s0[r] * SC2 + c4[e]; }
;                 }
;             if (__builtin_amdgcn_readfirstlane((int)fmask)) {
; #pragma unroll
;                 for (int r = 0; r < 16; ++r) {
;                     const int key = kbase + 8 * (r >> 2) + (r & 3);
;                     if (key > t) s0[r] = -INFINITY;
;                     if (key + 32 > t) s1[r] = -INFINITY;
;                 }
;             }
.LBB0_178:
	v_add_u32_e32 v14, v134, v135
	v_add_u32_e32 v0, v136, v135
	v_add_u32_e32 v156, v138, v139
	ds_read_b128 v[170:173], v14 offset:0
	ds_read_b128 v[178:181], v14 offset:32
	ds_read_b128 v[186:189], v14 offset:64
	ds_read_b128 v[198:201], v14 offset:96
	ds_read_b128 v[174:177], v0 offset:0
	ds_read_b128 v[182:185], v0 offset:32
	ds_read_b128 v[194:197], v0 offset:64
	ds_read_b128 v[202:205], v0 offset:96
	ds_read_b128 v[144:147], v135 offset:43008
	ds_read_b128 v[148:151], v135 offset:43040
	ds_read_b128 v[152:155], v135 offset:43072
	ds_read_b128 v[12:15], v135 offset:43104
	s_or_b32 s1, s0, 63
	v_cmp_gt_i32_e32 vcc, s1, v125
	s_waitcnt lgkmcnt(11)
	v_mfma_f32_32x32x16_bf16 v[80:95], v[170:173], v[104:107], v[48:63]
	ds_read_b64_tr_b16 v[206:207], v156 offset:18432
	ds_read_b64_tr_b16 v[208:209], v156 offset:19968
	s_waitcnt lgkmcnt(12)
	v_mfma_f32_32x32x16_bf16 v[80:95], v[178:181], v[96:99], v[80:95]
	ds_read_b64_tr_b16 v[210:211], v156 offset:21504
	ds_read_b64_tr_b16 v[212:213], v156 offset:23040
	s_waitcnt lgkmcnt(13)
	v_mfma_f32_32x32x16_bf16 v[80:95], v[186:189], v[100:103], v[80:95]
	ds_read_b64_tr_b16 v[226:227], v156 offset:24576
	ds_read_b64_tr_b16 v[228:229], v156 offset:26112
	s_waitcnt lgkmcnt(14)
	v_mfma_f32_32x32x16_bf16 v[80:95], v[198:201], v[108:111], v[80:95]
	ds_read_b64_tr_b16 v[230:231], v156 offset:27648
	ds_read_b64_tr_b16 v[232:233], v156 offset:29184
	ds_read_b128 v[170:173], v135 offset:43136
	ds_read_b128 v[178:181], v135 offset:43168
	ds_read_b128 v[186:189], v135 offset:43200
	ds_read_b128 v[198:201], v135 offset:43232
	s_waitcnt lgkmcnt(15)
	v_mfma_f32_32x32x16_bf16 v[64:79], v[174:177], v[104:107], v[48:63]
	ds_read_b64_tr_b16 v[234:235], v156 offset:18496
	ds_read_b64_tr_b16 v[236:237], v156 offset:20032
	s_waitcnt lgkmcnt(15)
	v_mfma_f32_32x32x16_bf16 v[64:79], v[182:185], v[96:99], v[64:79]
	ds_read_b64_tr_b16 v[238:239], v156 offset:21568
	ds_read_b64_tr_b16 v[240:241], v156 offset:23104
	v_fma_f32 v82, v82, s54, v146
	v_fma_f32 v83, v83, s54, v147
	v_fma_f32 v86, v86, s54, v150
	v_fma_f32 v87, v87, s54, v151
	v_fma_f32 v88, v88, s54, v152
	v_fma_f32 v89, v89, s54, v153
	v_cndmask_b32_e64 v0, 0, 1, vcc
	s_nop 0
	v_readfirstlane_b32 s1, v0
	s_bitcmp0_b32 s1, 0
	s_waitcnt lgkmcnt(15)
	v_mfma_f32_32x32x16_bf16 v[64:79], v[194:197], v[100:103], v[64:79]
	ds_read_b64_tr_b16 v[242:243], v156 offset:24640
	ds_read_b64_tr_b16 v[244:245], v156 offset:26176
	v_fma_f32 v10, v94, s54, v14
	v_fma_f32 v11, v95, s54, v15
	v_fma_f32 v12, v92, s54, v12
	v_fma_f32 v13, v93, s54, v13
	v_fma_f32 v14, v90, s54, v154
	v_fma_f32 v15, v91, s54, v155
	s_waitcnt lgkmcnt(15)
	v_mfma_f32_32x32x16_bf16 v[64:79], v[202:205], v[108:111], v[64:79]
	ds_read_b64_tr_b16 v[246:247], v156 offset:27712
	ds_read_b64_tr_b16 v[248:249], v156 offset:29248
	v_fma_f32 v84, v84, s54, v148
	v_fma_f32 v85, v85, s54, v149
	v_fma_f32 v80, v80, s54, v144
	v_fma_f32 v81, v81, s54, v145
	s_waitcnt lgkmcnt(8)
	s_nop 5
	v_fma_f32 v66, v66, s54, v172
	v_fma_f32 v67, v67, s54, v173
	v_fma_f32 v70, v70, s54, v180
	v_fma_f32 v71, v71, s54, v181
	v_fma_f32 v74, v74, s54, v188
	v_fma_f32 v75, v75, s54, v189
	v_fma_f32 v78, v78, s54, v200
	v_fma_f32 v79, v79, s54, v201
	v_fma_f32 v76, v76, s54, v198
	v_fma_f32 v77, v77, s54, v199
	v_fma_f32 v72, v72, s54, v186
	v_fma_f32 v73, v73, s54, v187
	v_fma_f32 v68, v68, s54, v178
	v_fma_f32 v69, v69, s54, v179
	v_fma_f32 v64, v64, s54, v170
	v_fma_f32 v65, v65, s54, v171
	s_cbranch_scc1 .LBB0_180
	v_or_b32_e32 v0, s0, v137
	v_or_b32_e32 v90, 32, v0
	v_cmp_le_i32_e32 vcc, v90, v126
	v_or_b32_e32 v90, 33, v0
	s_nop 0
	v_cndmask_b32_e32 v64, v220, v64, vcc
	v_cmp_lt_i32_e32 vcc, v0, v126
	s_nop 1
	v_cndmask_b32_e32 v81, v220, v81, vcc
	v_cmp_le_i32_e32 vcc, v0, v126
	s_nop 1
	v_cndmask_b32_e32 v80, v220, v80, vcc
	v_cmp_le_i32_e32 vcc, v90, v126
	v_or_b32_e32 v90, 2, v0
	s_nop 0
	v_cndmask_b32_e32 v65, v220, v65, vcc
	v_cmp_le_i32_e32 vcc, v90, v126
	v_or_b32_e32 v90, 34, v0
	s_nop 0
	v_cndmask_b32_e32 v82, v220, v82, vcc
	v_cmp_le_i32_e32 vcc, v90, v126
	v_or_b32_e32 v90, 3, v0
	s_nop 0
	v_cndmask_b32_e32 v66, v220, v66, vcc
	v_cmp_le_i32_e32 vcc, v90, v126
	v_or_b32_e32 v90, 35, v0
	s_nop 0
	v_cndmask_b32_e32 v83, v220, v83, vcc
	v_cmp_le_i32_e32 vcc, v90, v126
	v_or_b32_e32 v90, 8, v0
	s_nop 0
	v_cndmask_b32_e32 v67, v220, v67, vcc
	v_cmp_le_i32_e32 vcc, v90, v126
	v_or_b32_e32 v90, 40, v0
	s_nop 0
	v_cndmask_b32_e32 v84, v220, v84, vcc
	v_cmp_le_i32_e32 vcc, v90, v126
	v_or_b32_e32 v90, 9, v0
	s_nop 0
	v_cndmask_b32_e32 v68, v220, v68, vcc
	v_cmp_le_i32_e32 vcc, v90, v126
	v_or_b32_e32 v90, 41, v0
	s_nop 0
	v_cndmask_b32_e32 v85, v220, v85, vcc
	v_cmp_le_i32_e32 vcc, v90, v126
	v_or_b32_e32 v90, 10, v0
	s_nop 0
	v_cndmask_b32_e32 v69, v220, v69, vcc
	v_cmp_le_i32_e32 vcc, v90, v126
	v_or_b32_e32 v90, 42, v0
	s_nop 0
	v_cndmask_b32_e32 v86, v220, v86, vcc
	v_cmp_le_i32_e32 vcc, v90, v126
	v_or_b32_e32 v90, 11, v0
	s_nop 0
	v_cndmask_b32_e32 v70, v220, v70, vcc
	v_cmp_le_i32_e32 vcc, v90, v126
	v_or_b32_e32 v90, 43, v0
	s_nop 0
	v_cndmask_b32_e32 v87, v220, v87, vcc
	v_cmp_le_i32_e32 vcc, v90, v126
	v_or_b32_e32 v90, 16, v0
	s_nop 0
	v_cndmask_b32_e32 v71, v220, v71, vcc
	v_cmp_le_i32_e32 vcc, v90, v126
	v_or_b32_e32 v90, 48, v0
	s_nop 0
	v_cndmask_b32_e32 v88, v220, v88, vcc
	v_cmp_le_i32_e32 vcc, v90, v126
	v_or_b32_e32 v90, 17, v0
	s_nop 0
	v_cndmask_b32_e32 v72, v220, v72, vcc
	v_cmp_le_i32_e32 vcc, v90, v126
	v_or_b32_e32 v90, 49, v0
	s_nop 0
	v_cndmask_b32_e32 v89, v220, v89, vcc
	v_cmp_le_i32_e32 vcc, v90, v126
	v_or_b32_e32 v90, 18, v0
	s_nop 0
	v_cndmask_b32_e32 v73, v220, v73, vcc
	v_cmp_le_i32_e32 vcc, v90, v126
	v_or_b32_e32 v90, 50, v0
	s_nop 0
	v_cndmask_b32_e32 v14, v220, v14, vcc
	v_cmp_le_i32_e32 vcc, v90, v126
	v_or_b32_e32 v90, 19, v0
	s_nop 0
	v_cndmask_b32_e32 v74, v220, v74, vcc
	v_cmp_le_i32_e32 vcc, v90, v126
	v_or_b32_e32 v90, 51, v0
	s_nop 0
	v_cndmask_b32_e32 v15, v220, v15, vcc
	v_cmp_le_i32_e32 vcc, v90, v126
	v_or_b32_e32 v90, 24, v0
	s_nop 0
	v_cndmask_b32_e32 v75, v220, v75, vcc
	v_cmp_le_i32_e32 vcc, v90, v126
	v_or_b32_e32 v90, 56, v0
	s_nop 0
	v_cndmask_b32_e32 v12, v220, v12, vcc
	v_cmp_le_i32_e32 vcc, v90, v126
	v_or_b32_e32 v90, 25, v0
	s_nop 0
	v_cndmask_b32_e32 v76, v220, v76, vcc
	v_cmp_le_i32_e32 vcc, v90, v126
	v_or_b32_e32 v90, 57, v0
	s_nop 0
	v_cndmask_b32_e32 v13, v220, v13, vcc
	v_cmp_le_i32_e32 vcc, v90, v126
	v_or_b32_e32 v90, 26, v0
	s_nop 0
	v_cndmask_b32_e32 v77, v220, v77, vcc
	v_cmp_le_i32_e32 vcc, v90, v126
	v_or_b32_e32 v90, 58, v0
	s_nop 0
	v_cndmask_b32_e32 v10, v220, v10, vcc
	v_cmp_le_i32_e32 vcc, v90, v126
	v_or_b32_e32 v90, 27, v0
	v_or_b32_e32 v0, 59, v0
	v_cndmask_b32_e32 v78, v220, v78, vcc
	v_cmp_le_i32_e32 vcc, v90, v126
	s_nop 1
	v_cndmask_b32_e32 v11, v220, v11, vcc
	v_cmp_le_i32_e32 vcc, v0, v126
	s_nop 1
	v_cndmask_b32_e32 v79, v220, v79, vcc

; __device__ __forceinline__ f32x16 mfma32(bf16x8 a, bf16x8 b, f32x16 c) { return __builtin_amdgcn_mfma_f32_32x32x16_bf16(a, b, c, 0, 0, 0); }
; template <int MODE> ...
;     ...
;         const lptr Kt = L + A_KT + buf * 9216, Vt = L + A_VT + vcur * 12288;
;         f32x16 s0, s1;
; #pragma unroll
;         for (int s4 = 0; s4 < 4; ++s4) {
;             const bf16x8 a0 = lds_ld<bf16x8>(Kt + n * KP + s4 * 32 + hl * 16);
;             const bf16x8 a1 = lds_ld<bf16x8>(Kt + (32 + n) * KP + s4 * 32 + hl * 16);
;             if (s4 == 0) { s0 = mfma32(a0, qf[0], negm); s1 = mfma32(a1, qf[0], negm); }
;             else { s0 = mfma32(a0, qf[s4], s0); s1 = mfma32(a1, qf[s4], s1); }
;         }
;         const int kbase = 64 * kt + 4 * hl;
;         const bool far = (MODE == MODE_WIN || MODE == MODE_SEL) ? (wtmin - (64 * kt + 63) >= 128) : false;
;         const bool fmask = (MODE == MODE_FOX) ? (64 * kt + 63 > wtmin) : false;
;         const bool clean = (MODE == MODE_WIN) ? (far && (wtmax - 64 * kt < W)) : false;
;         const float mref = (MODE == MODE_CMP2) ? mfix : ((m == -INFINITY) ? 0.f : m);
;         if (MODE == MODE_FOX) {
; #pragma unroll
;             for (int kb = 0; kb < 2; ++kb)
; #pragma unroll
;                 for (int a = 0; a < 4; ++a) {
;                     const f32x4 c4 = lds_ld<f32x4>(L + A_CB + buf * 256 + (32 * kb + 8 * a + 4 * hl) * 4);
; #pragma unroll
;                     for (int e = 0; e < 4; ++e) { const int r = 4 * a + e; if (kb) s1[r] = s1[r] * SC2 + c4[e]; else s0[r] = s0[r] * SC2 + c4[e]; }
;                 }
;             if (__builtin_amdgcn_readfirstlane((int)fmask)) {
; #pragma unroll
;                 for (int r = 0; r < 16; ++r) {
;                     const int key = kbase + 8 * (r >> 2) + (r & 3);
;                     if (key > t) s0[r] = -INFINITY;
;                     if (key + 32 > t) s1[r] = -INFINITY;
;                 }
;             }
.LBB0_194:
	v_add_u32_e32 v14, v134, v135
	v_add_u32_e32 v0, v136, v135
	v_add_u32_e32 v156, v138, v139
	ds_read_b128 v[170:173], v14 offset:9216
	ds_read_b128 v[178:181], v14 offset:9248
	ds_read_b128 v[186:189], v14 offset:9280
	ds_read_b128 v[198:201], v14 offset:9312
	ds_read_b128 v[174:177], v0 offset:9216
	ds_read_b128 v[182:185], v0 offset:9248
	ds_read_b128 v[194:197], v0 offset:9280
	ds_read_b128 v[202:205], v0 offset:9312
	ds_read_b128 v[144:147], v135 offset:43264
	ds_read_b128 v[148:151], v135 offset:43296
	ds_read_b128 v[152:155], v135 offset:43328
	ds_read_b128 v[12:15], v135 offset:43360
	s_or_b32 s1, s0, 63
	v_cmp_gt_i32_e32 vcc, s1, v125
	s_waitcnt lgkmcnt(11)
	v_mfma_f32_32x32x16_bf16 v[80:95], v[170:173], v[104:107], v[48:63]
	ds_read_b64_tr_b16 v[206:207], v156 offset:30720
	ds_read_b64_tr_b16 v[208:209], v156 offset:32256
	s_waitcnt lgkmcnt(12)
	v_mfma_f32_32x32x16_bf16 v[80:95], v[178:181], v[96:99], v[80:95]
	ds_read_b64_tr_b16 v[210:211], v156 offset:33792
	ds_read_b64_tr_b16 v[212:213], v156 offset:35328
	s_waitcnt lgkmcnt(13)
	v_mfma_f32_32x32x16_bf16 v[80:95], v[186:189], v[100:103], v[80:95]
	ds_read_b64_tr_b16 v[226:227], v156 offset:36864
	ds_read_b64_tr_b16 v[228:229], v156 offset:38400
	s_waitcnt lgkmcnt(14)
	v_mfma_f32_32x32x16_bf16 v[80:95], v[198:201], v[108:111], v[80:95]
	ds_read_b64_tr_b16 v[230:231], v156 offset:39936
	ds_read_b64_tr_b16 v[232:233], v156 offset:41472
	ds_read_b128 v[170:173], v135 offset:43392
	ds_read_b128 v[178:181], v135 offset:43424
	ds_read_b128 v[186:189], v135 offset:43456
	ds_read_b128 v[198:201], v135 offset:43488
	s_waitcnt lgkmcnt(15)
	v_mfma_f32_32x32x16_bf16 v[64:79], v[174:177], v[104:107], v[48:63]
	ds_read_b64_tr_b16 v[234:235], v156 offset:30784
	ds_read_b64_tr_b16 v[236:237], v156 offset:32320
	s_waitcnt lgkmcnt(15)
	v_mfma_f32_32x32x16_bf16 v[64:79], v[182:185], v[96:99], v[64:79]
	ds_read_b64_tr_b16 v[238:239], v156 offset:33856
	ds_read_b64_tr_b16 v[240:241], v156 offset:35392
	v_fma_f32 v82, v82, s54, v146
	v_fma_f32 v83, v83, s54, v147
	v_fma_f32 v86, v86, s54, v150
	v_fma_f32 v87, v87, s54, v151
	v_fma_f32 v88, v88, s54, v152
	v_fma_f32 v89, v89, s54, v153
	v_cndmask_b32_e64 v0, 0, 1, vcc
	s_nop 0
	v_readfirstlane_b32 s1, v0
	s_bitcmp0_b32 s1, 0
	s_waitcnt lgkmcnt(15)
	v_mfma_f32_32x32x16_bf16 v[64:79], v[194:197], v[100:103], v[64:79]
	ds_read_b64_tr_b16 v[242:243], v156 offset:36928
	ds_read_b64_tr_b16 v[244:245], v156 offset:38464
	v_fma_f32 v10, v94, s54, v14
	v_fma_f32 v11, v95, s54, v15
	v_fma_f32 v12, v92, s54, v12
	v_fma_f32 v13, v93, s54, v13
	v_fma_f32 v14, v90, s54, v154
	v_fma_f32 v15, v91, s54, v155
	s_waitcnt lgkmcnt(15)
	v_mfma_f32_32x32x16_bf16 v[64:79], v[202:205], v[108:111], v[64:79]
	ds_read_b64_tr_b16 v[246:247], v156 offset:40000
	ds_read_b64_tr_b16 v[248:249], v156 offset:41536
	v_fma_f32 v84, v84, s54, v148
	v_fma_f32 v85, v85, s54, v149
	v_fma_f32 v80, v80, s54, v144
	v_fma_f32 v81, v81, s54, v145
	s_waitcnt lgkmcnt(8)
	s_nop 5
	v_fma_f32 v66, v66, s54, v172
	v_fma_f32 v67, v67, s54, v173
	v_fma_f32 v70, v70, s54, v180
	v_fma_f32 v71, v71, s54, v181
	v_fma_f32 v74, v74, s54, v188
	v_fma_f32 v75, v75, s54, v189
	v_fma_f32 v78, v78, s54, v200
	v_fma_f32 v79, v79, s54, v201
	v_fma_f32 v76, v76, s54, v198
	v_fma_f32 v77, v77, s54, v199
	v_fma_f32 v72, v72, s54, v186
	v_fma_f32 v73, v73, s54, v187
	v_fma_f32 v68, v68, s54, v178
	v_fma_f32 v69, v69, s54, v179
	v_fma_f32 v64, v64, s54, v170
	v_fma_f32 v65, v65, s54, v171
	s_cbranch_scc1 .LBB0_196
	v_or_b32_e32 v0, s0, v137
	v_or_b32_e32 v90, 32, v0
	v_cmp_le_i32_e32 vcc, v90, v126
	v_or_b32_e32 v90, 33, v0
	s_nop 0
	v_cndmask_b32_e32 v64, v220, v64, vcc
	v_cmp_lt_i32_e32 vcc, v0, v126
	s_nop 1
	v_cndmask_b32_e32 v81, v220, v81, vcc
	v_cmp_le_i32_e32 vcc, v0, v126
	s_nop 1
	v_cndmask_b32_e32 v80, v220, v80, vcc
	v_cmp_le_i32_e32 vcc, v90, v126
	v_or_b32_e32 v90, 2, v0
	s_nop 0
	v_cndmask_b32_e32 v65, v220, v65, vcc
	v_cmp_le_i32_e32 vcc, v90, v126
	v_or_b32_e32 v90, 34, v0
	s_nop 0
	v_cndmask_b32_e32 v82, v220, v82, vcc
	v_cmp_le_i32_e32 vcc, v90, v126
	v_or_b32_e32 v90, 3, v0
	s_nop 0
	v_cndmask_b32_e32 v66, v220, v66, vcc
	v_cmp_le_i32_e32 vcc, v90, v126
	v_or_b32_e32 v90, 35, v0
	s_nop 0
	v_cndmask_b32_e32 v83, v220, v83, vcc
	v_cmp_le_i32_e32 vcc, v90, v126
	v_or_b32_e32 v90, 8, v0
	s_nop 0
	v_cndmask_b32_e32 v67, v220, v67, vcc
	v_cmp_le_i32_e32 vcc, v90, v126
	v_or_b32_e32 v90, 40, v0
	s_nop 0
	v_cndmask_b32_e32 v84, v220, v84, vcc
	v_cmp_le_i32_e32 vcc, v90, v126
	v_or_b32_e32 v90, 9, v0
	s_nop 0
	v_cndmask_b32_e32 v68, v220, v68, vcc
	v_cmp_le_i32_e32 vcc, v90, v126
	v_or_b32_e32 v90, 41, v0
	s_nop 0
	v_cndmask_b32_e32 v85, v220, v85, vcc
	v_cmp_le_i32_e32 vcc, v90, v126
	v_or_b32_e32 v90, 10, v0
	s_nop 0
	v_cndmask_b32_e32 v69, v220, v69, vcc
	v_cmp_le_i32_e32 vcc, v90, v126
	v_or_b32_e32 v90, 42, v0
	s_nop 0
	v_cndmask_b32_e32 v86, v220, v86, vcc
	v_cmp_le_i32_e32 vcc, v90, v126
	v_or_b32_e32 v90, 11, v0
	s_nop 0
	v_cndmask_b32_e32 v70, v220, v70, vcc
	v_cmp_le_i32_e32 vcc, v90, v126
	v_or_b32_e32 v90, 43, v0
	s_nop 0
	v_cndmask_b32_e32 v87, v220, v87, vcc
	v_cmp_le_i32_e32 vcc, v90, v126
	v_or_b32_e32 v90, 16, v0
	s_nop 0
	v_cndmask_b32_e32 v71, v220, v71, vcc
	v_cmp_le_i32_e32 vcc, v90, v126
	v_or_b32_e32 v90, 48, v0
	s_nop 0
	v_cndmask_b32_e32 v88, v220, v88, vcc
	v_cmp_le_i32_e32 vcc, v90, v126
	v_or_b32_e32 v90, 17, v0
	s_nop 0
	v_cndmask_b32_e32 v72, v220, v72, vcc
	v_cmp_le_i32_e32 vcc, v90, v126
	v_or_b32_e32 v90, 49, v0
	s_nop 0
	v_cndmask_b32_e32 v89, v220, v89, vcc
	v_cmp_le_i32_e32 vcc, v90, v126
	v_or_b32_e32 v90, 18, v0
	s_nop 0
	v_cndmask_b32_e32 v73, v220, v73, vcc
	v_cmp_le_i32_e32 vcc, v90, v126
	v_or_b32_e32 v90, 50, v0
	s_nop 0
	v_cndmask_b32_e32 v14, v220, v14, vcc
	v_cmp_le_i32_e32 vcc, v90, v126
	v_or_b32_e32 v90, 19, v0
	s_nop 0
	v_cndmask_b32_e32 v74, v220, v74, vcc
	v_cmp_le_i32_e32 vcc, v90, v126
	v_or_b32_e32 v90, 51, v0
	s_nop 0
	v_cndmask_b32_e32 v15, v220, v15, vcc
	v_cmp_le_i32_e32 vcc, v90, v126
	v_or_b32_e32 v90, 24, v0
	s_nop 0
	v_cndmask_b32_e32 v75, v220, v75, vcc
	v_cmp_le_i32_e32 vcc, v90, v126
	v_or_b32_e32 v90, 56, v0
	s_nop 0
	v_cndmask_b32_e32 v12, v220, v12, vcc
	v_cmp_le_i32_e32 vcc, v90, v126
	v_or_b32_e32 v90, 25, v0
	s_nop 0
	v_cndmask_b32_e32 v76, v220, v76, vcc
	v_cmp_le_i32_e32 vcc, v90, v126
	v_or_b32_e32 v90, 57, v0
	s_nop 0
	v_cndmask_b32_e32 v13, v220, v13, vcc
	v_cmp_le_i32_e32 vcc, v90, v126
	v_or_b32_e32 v90, 26, v0
	s_nop 0
	v_cndmask_b32_e32 v77, v220, v77, vcc
	v_cmp_le_i32_e32 vcc, v90, v126
	v_or_b32_e32 v90, 58, v0
	s_nop 0
	v_cndmask_b32_e32 v10, v220, v10, vcc
	v_cmp_le_i32_e32 vcc, v90, v126
	v_or_b32_e32 v90, 27, v0
	v_or_b32_e32 v0, 59, v0
	v_cndmask_b32_e32 v78, v220, v78, vcc
	v_cmp_le_i32_e32 vcc, v90, v126
	s_nop 1
	v_cndmask_b32_e32 v11, v220, v11, vcc
	v_cmp_le_i32_e32 vcc, v0, v126
	s_nop 1
	v_cndmask_b32_e32 v79, v220, v79, vcc
